# layer-1 fp4 table conversion moved from P13 to P15/P17 GEMM tails, only on CUs whose both blocks are idle
# speedup vs baseline: 1.0094x; 1.0094x over previous
.LBB0_2653:
	v_readlane_b32 s0, v245, 0
	s_lshl_b32 s0, s0, 2
	v_lshrrev_b32_e32 v2, 6, v1
	s_addk_i32 s0, 0x7c00
	v_add_u32_e32 v2, s0, v2
	v_add_u32_e32 v2, 0x20000, v2
	s_mov_b32 s0, 0x10000
	v_cmp_gt_i32_e32 vcc, s0, v2
	v_readlane_b32 s1, v245, 1
	s_and_saveexec_b64 s[2:3], vcc
	s_cbranch_execz .LBB0_2658
	v_readlane_b32 s8, v245, 7
	v_readlane_b32 s10, v245, 9
	v_ashrrev_i32_e32 v3, 31, v2
	s_waitcnt vmcnt(10)
	v_and_b32_e32 v10, 63, v1
	s_lshl_b32 s4, s10, 2
	s_waitcnt vmcnt(9)
	v_lshlrev_b64 v[8:9], 9, v[2:3]
	v_readlane_b32 s9, v245, 8
	s_addk_i32 s4, 0xfc00
	v_lshl_or_b32 v8, v10, 3, v8
	v_lshl_add_u64 v[6:7], v[2:3], 2, s[50:51]
	s_mov_b64 s[6:7], 0xa310800
	s_ashr_i32 s5, s4, 31
	v_lshl_add_u64 v[8:9], s[50:51], 0, v[8:9]
	s_mov_b64 s[8:9], 0x4280000
	v_lshlrev_b32_e32 v4, 2, v10
	v_mov_b32_e32 v5, 0
	v_readlane_b32 s11, v245, 10
	v_lshl_add_u64 v[6:7], v[6:7], 0, s[6:7]
	s_lshl_b64 s[6:7], s[4:5], 2
	v_lshl_add_u64 v[8:9], v[8:9], 0, s[8:9]
	s_lshl_b64 s[8:9], s[4:5], 9
	s_lshl_b32 s5, s10, 12
	v_cmp_eq_u32_e64 s[0:1], 0, v10
	v_lshlrev_b32_e32 v3, 10, v2
	s_add_i32 s5, s5, 0xfff00000
	s_mov_b64 s[10:11], 0
	v_mov_b32_e32 v12, s47
	v_mov_b32_e32 v13, s45
	v_mov_b32_e32 v14, s46
	v_mov_b32_e32 v15, s44
	v_lshlrev_b32_e32 v10, 4, v4
	v_mov_b32_e32 v11, v5
	s_mov_b32 s14, 0x40c00000
	s_mov_b32 s15, 0xffff
	s_branch .LBB0_2656

.Ltc_p15:
	s_mov_b64 exec, -1
	v_readlane_b32 s84, v245, 0
	s_nop 3
	s_and_b32 s97, s84, 0xff
	s_cmp_lt_u32 s97, 40
	s_cbranch_scc1 .Ltc_p15_end
	v_and_b32_e32 v255, 63, v0
	v_lshlrev_b32_e32 v254, 6, v255
	v_lshlrev_b32_e32 v255, 3, v255
	v_mov_b32_e32 v251, 0
	v_readfirstlane_b32 s96, v0
	v_readlane_b32 s98, v244, 22
	v_readlane_b32 s99, v244, 23
	v_readlane_b32 s100, v244, 24
	v_readlane_b32 s101, v244, 25
	s_nop 3
	s_and_b32 s96, s96, 0x3ff
	s_lshr_b32 s96, s96, 6
	s_sub_u32 s97, s97, 40
	s_lshr_b32 s84, s84, 8
	s_mul_i32 s84, s84, 216
	s_add_u32 s84, s84, s97
	s_lshl_b32 s84, s84, 2
	s_add_u32 s84, s84, s96
	s_add_u32 s84, s84, 0x8000
	s_mov_b32 s85, 1728
	s_mov_b32 s91, 0x40c00000
	s_cmp_ge_u32 s84, 0xc900
	s_cbranch_scc1 .Ltc_p15_end
	s_mov_b32 s90, s84
.Ltc_p15_last:
	s_add_u32 s87, s90, s85
	s_cmp_ge_u32 s87, 0xc900
	s_cbranch_scc1 .Ltc_p15_lastd
	s_mov_b32 s90, s87
	s_branch .Ltc_p15_last
.Ltc_p15_lastd:
	s_mov_b32 s86, s84
	s_and_b32 s96, s86, 0x4000
	s_cmp_eq_u32 s96, 0
	s_cselect_b32 s94, s98, s100
	s_cselect_b32 s95, s99, s101
	s_and_b32 s96, s86, 0x3fff
	s_lshl_b32 s96, s96, 12
	s_add_u32 s94, s94, s96
	s_addc_u32 s95, s95, 0
	s_lshr_b32 s96, s86, 15
	s_lshl_b32 s96, s96, 26
	s_add_u32 s94, s94, s96
	s_addc_u32 s95, s95, 0
	global_load_dwordx4 v[176:179], v254, s[94:95] nt
	global_load_dwordx4 v[180:183], v254, s[94:95] offset:16 nt
	global_load_dwordx4 v[184:187], v254, s[94:95] offset:32 nt
	global_load_dwordx4 v[188:191], v254, s[94:95] offset:48 nt
	global_load_dword v175, v255, s[98:99]
	global_load_dword v175, v255, s[98:99]
	s_add_u32 s86, s86, s85
	s_min_u32 s87, s86, s90
	s_and_b32 s96, s87, 0x4000
	s_cmp_eq_u32 s96, 0
	s_cselect_b32 s94, s98, s100
	s_cselect_b32 s95, s99, s101
	s_and_b32 s96, s87, 0x3fff
	s_lshl_b32 s96, s96, 12
	s_add_u32 s94, s94, s96
	s_addc_u32 s95, s95, 0
	s_lshr_b32 s96, s87, 15
	s_lshl_b32 s96, s96, 26
	s_add_u32 s94, s94, s96
	s_addc_u32 s95, s95, 0
	global_load_dwordx4 v[192:195], v254, s[94:95] nt
	global_load_dwordx4 v[196:199], v254, s[94:95] offset:16 nt
	global_load_dwordx4 v[200:203], v254, s[94:95] offset:32 nt
	global_load_dwordx4 v[204:207], v254, s[94:95] offset:48 nt
	global_load_dword v175, v255, s[98:99]
	global_load_dword v175, v255, s[98:99]
	s_add_u32 s86, s86, s85
	s_min_u32 s87, s86, s90
	s_and_b32 s96, s87, 0x4000
	s_cmp_eq_u32 s96, 0
	s_cselect_b32 s94, s98, s100
	s_cselect_b32 s95, s99, s101
	s_and_b32 s96, s87, 0x3fff
	s_lshl_b32 s96, s96, 12
	s_add_u32 s94, s94, s96
	s_addc_u32 s95, s95, 0
	s_lshr_b32 s96, s87, 15
	s_lshl_b32 s96, s96, 26
	s_add_u32 s94, s94, s96
	s_addc_u32 s95, s95, 0
	global_load_dwordx4 v[208:211], v254, s[94:95] nt
	global_load_dwordx4 v[212:215], v254, s[94:95] offset:16 nt
	global_load_dwordx4 v[216:219], v254, s[94:95] offset:32 nt
	global_load_dwordx4 v[220:223], v254, s[94:95] offset:48 nt
.Ltc_p15_loop:
	s_cmp_ge_u32 s84, 0xc900
	s_cbranch_scc1 .Ltc_p15_done
	s_waitcnt vmcnt(12)
	v_max_f32_e64 v240, |v176|, |v177|
	v_max3_f32 v240, |v178|, |v179|, v240
	v_max3_f32 v240, |v180|, |v181|, v240
	v_max3_f32 v240, |v182|, |v183|, v240
	v_max3_f32 v240, |v184|, |v185|, v240
	v_max3_f32 v240, |v186|, |v187|, v240
	v_max3_f32 v240, |v188|, |v189|, v240
	v_max3_f32 v240, |v190|, |v191|, v240
	s_nop 1
	v_mov_b32_dpp v241, v240 quad_perm:[1,0,3,2] row_mask:0xf bank_mask:0xf bound_ctrl:1
	v_max_f32_e32 v241, v241, v241
	v_max_f32_e32 v240, v240, v241
	s_nop 1
	v_mov_b32_dpp v241, v240 quad_perm:[2,3,0,1] row_mask:0xf bank_mask:0xf bound_ctrl:1
	v_max_f32_e32 v241, v241, v241
	v_max_f32_e32 v240, v240, v241
	s_nop 1
	v_mov_b32_dpp v241, v240 row_half_mirror row_mask:0xf bank_mask:0xf bound_ctrl:1
	v_max_f32_e32 v241, v241, v241
	v_max_f32_e32 v240, v240, v241
	s_nop 1
	v_mov_b32_dpp v241, v240 row_mirror row_mask:0xf bank_mask:0xf bound_ctrl:1
	v_max_f32_e32 v241, v241, v241
	v_max_f32_e32 v240, v240, v241
	s_nop 0
	v_readlane_b32 s96, v240, 32
	v_readlane_b32 s97, v240, 48
	v_readlane_b32 s92, v240, 0
	v_readlane_b32 s93, v240, 16
	s_nop 1
	v_max_f32_e64 v240, s97, s97
	v_max_f32_e64 v241, s96, s96
	v_mov_b32_e32 v248, s93
	v_max_f32_e32 v240, v241, v240
	v_max3_f32 v240, s92, v248, v240
	v_div_scale_f32 v243, s[92:93], v240, v240, s91
	v_rcp_f32_e32 v246, v243
	v_div_scale_f32 v247, vcc, s91, v240, s91
	v_fma_f32 v248, -v243, v246, 1.0
	v_fmac_f32_e32 v246, v248, v246
	v_mul_f32_e32 v249, v247, v246
	v_fma_f32 v248, -v243, v249, v247
	v_fmac_f32_e32 v249, v248, v246
	v_fma_f32 v248, -v243, v249, v247
	v_div_fmas_f32 v242, v248, v246, v249
	v_div_fixup_f32 v242, v242, v240, s91
	v_cmp_lt_f32_e32 vcc, 0, v240
	v_mov_b32_e32 v252, 0
	v_mov_b32_e32 v253, 0
	v_cndmask_b32_e32 v242, 0, v242, vcc
	v_mul_f32_e32 v250, 0x3e2aaaab, v240
	v_mul_f32_e32 v176, v176, v242
	v_mul_f32_e32 v177, v177, v242
	v_mul_f32_e32 v178, v178, v242
	v_mul_f32_e32 v179, v179, v242
	v_mul_f32_e32 v180, v180, v242
	v_mul_f32_e32 v181, v181, v242
	v_mul_f32_e32 v182, v182, v242
	v_mul_f32_e32 v183, v183, v242
	v_mul_f32_e32 v184, v184, v242
	v_mul_f32_e32 v185, v185, v242
	v_mul_f32_e32 v186, v186, v242
	v_mul_f32_e32 v187, v187, v242
	v_mul_f32_e32 v188, v188, v242
	v_mul_f32_e32 v189, v189, v242
	v_mul_f32_e32 v190, v190, v242
	v_mul_f32_e32 v191, v191, v242
	v_cvt_scalef32_pk_fp4_f32 v252, v176, v177, 1.0
	v_cvt_scalef32_pk_fp4_f32 v253, v184, v185, 1.0
	v_cvt_scalef32_pk_fp4_f32 v252, v178, v179, 1.0 op_sel:[0,0,1,0]
	v_cvt_scalef32_pk_fp4_f32 v253, v186, v187, 1.0 op_sel:[0,0,1,0]
	v_cvt_scalef32_pk_fp4_f32 v252, v180, v181, 1.0 op_sel:[0,0,0,1]
	v_cvt_scalef32_pk_fp4_f32 v253, v188, v189, 1.0 op_sel:[0,0,0,1]
	v_cvt_scalef32_pk_fp4_f32 v252, v182, v183, 1.0 op_sel:[0,0,1,1]
	v_cvt_scalef32_pk_fp4_f32 v253, v190, v191, 1.0 op_sel:[0,0,1,1]
	v_readlane_b32 s88, v244, 28
	v_readlane_b32 s89, v244, 29
	s_lshl_b32 s96, s84, 9
	s_nop 1
	s_add_u32 s88, s88, 0x4280000
	s_addc_u32 s89, s89, 0
	s_add_u32 s88, s88, s96
	s_addc_u32 s89, s89, 0
	s_nop 0
	global_store_dwordx2 v255, v[252:253], s[88:89]
	v_readlane_b32 s88, v244, 28
	v_readlane_b32 s89, v244, 29
	s_lshl_b32 s96, s84, 2
	s_nop 1
	s_add_u32 s88, s88, 0xa310800
	s_addc_u32 s89, s89, 0
	s_add_u32 s88, s88, s96
	s_addc_u32 s89, s89, 0
	s_mov_b64 exec, 1
	global_store_dword v251, v250, s[88:89]
	s_mov_b64 exec, -1
	s_add_u32 s86, s86, s85
	s_min_u32 s87, s86, s90
	s_and_b32 s96, s87, 0x4000
	s_cmp_eq_u32 s96, 0
	s_cselect_b32 s94, s98, s100
	s_cselect_b32 s95, s99, s101
	s_and_b32 s96, s87, 0x3fff
	s_lshl_b32 s96, s96, 12
	s_add_u32 s94, s94, s96
	s_addc_u32 s95, s95, 0
	s_lshr_b32 s96, s87, 15
	s_lshl_b32 s96, s96, 26
	s_add_u32 s94, s94, s96
	s_addc_u32 s95, s95, 0
	global_load_dwordx4 v[224:227], v254, s[94:95] nt
	global_load_dwordx4 v[228:231], v254, s[94:95] offset:16 nt
	global_load_dwordx4 v[232:235], v254, s[94:95] offset:32 nt
	global_load_dwordx4 v[236:239], v254, s[94:95] offset:48 nt
	s_add_u32 s84, s84, s85
	s_cmp_ge_u32 s84, 0xc900
	s_cbranch_scc1 .Ltc_p15_done
	s_waitcnt vmcnt(12)
	v_max_f32_e64 v240, |v192|, |v193|
	v_max3_f32 v240, |v194|, |v195|, v240
	v_max3_f32 v240, |v196|, |v197|, v240
	v_max3_f32 v240, |v198|, |v199|, v240
	v_max3_f32 v240, |v200|, |v201|, v240
	v_max3_f32 v240, |v202|, |v203|, v240
	v_max3_f32 v240, |v204|, |v205|, v240
	v_max3_f32 v240, |v206|, |v207|, v240
	s_nop 1
	v_mov_b32_dpp v241, v240 quad_perm:[1,0,3,2] row_mask:0xf bank_mask:0xf bound_ctrl:1
	v_max_f32_e32 v241, v241, v241
	v_max_f32_e32 v240, v240, v241
	s_nop 1
	v_mov_b32_dpp v241, v240 quad_perm:[2,3,0,1] row_mask:0xf bank_mask:0xf bound_ctrl:1
	v_max_f32_e32 v241, v241, v241
	v_max_f32_e32 v240, v240, v241
	s_nop 1
	v_mov_b32_dpp v241, v240 row_half_mirror row_mask:0xf bank_mask:0xf bound_ctrl:1
	v_max_f32_e32 v241, v241, v241
	v_max_f32_e32 v240, v240, v241
	s_nop 1
	v_mov_b32_dpp v241, v240 row_mirror row_mask:0xf bank_mask:0xf bound_ctrl:1
	v_max_f32_e32 v241, v241, v241
	v_max_f32_e32 v240, v240, v241
	s_nop 0
	v_readlane_b32 s96, v240, 32
	v_readlane_b32 s97, v240, 48
	v_readlane_b32 s92, v240, 0
	v_readlane_b32 s93, v240, 16
	s_nop 1
	v_max_f32_e64 v240, s97, s97
	v_max_f32_e64 v241, s96, s96
	v_mov_b32_e32 v248, s93
	v_max_f32_e32 v240, v241, v240
	v_max3_f32 v240, s92, v248, v240
	v_div_scale_f32 v243, s[92:93], v240, v240, s91
	v_rcp_f32_e32 v246, v243
	v_div_scale_f32 v247, vcc, s91, v240, s91
	v_fma_f32 v248, -v243, v246, 1.0
	v_fmac_f32_e32 v246, v248, v246
	v_mul_f32_e32 v249, v247, v246
	v_fma_f32 v248, -v243, v249, v247
	v_fmac_f32_e32 v249, v248, v246
	v_fma_f32 v248, -v243, v249, v247
	v_div_fmas_f32 v242, v248, v246, v249
	v_div_fixup_f32 v242, v242, v240, s91
	v_cmp_lt_f32_e32 vcc, 0, v240
	v_mov_b32_e32 v252, 0
	v_mov_b32_e32 v253, 0
	v_cndmask_b32_e32 v242, 0, v242, vcc
	v_mul_f32_e32 v250, 0x3e2aaaab, v240
	v_mul_f32_e32 v192, v192, v242
	v_mul_f32_e32 v193, v193, v242
	v_mul_f32_e32 v194, v194, v242
	v_mul_f32_e32 v195, v195, v242
	v_mul_f32_e32 v196, v196, v242
	v_mul_f32_e32 v197, v197, v242
	v_mul_f32_e32 v198, v198, v242
	v_mul_f32_e32 v199, v199, v242
	v_mul_f32_e32 v200, v200, v242
	v_mul_f32_e32 v201, v201, v242
	v_mul_f32_e32 v202, v202, v242
	v_mul_f32_e32 v203, v203, v242
	v_mul_f32_e32 v204, v204, v242
	v_mul_f32_e32 v205, v205, v242
	v_mul_f32_e32 v206, v206, v242
	v_mul_f32_e32 v207, v207, v242
	v_cvt_scalef32_pk_fp4_f32 v252, v192, v193, 1.0
	v_cvt_scalef32_pk_fp4_f32 v253, v200, v201, 1.0
	v_cvt_scalef32_pk_fp4_f32 v252, v194, v195, 1.0 op_sel:[0,0,1,0]
	v_cvt_scalef32_pk_fp4_f32 v253, v202, v203, 1.0 op_sel:[0,0,1,0]
	v_cvt_scalef32_pk_fp4_f32 v252, v196, v197, 1.0 op_sel:[0,0,0,1]
	v_cvt_scalef32_pk_fp4_f32 v253, v204, v205, 1.0 op_sel:[0,0,0,1]
	v_cvt_scalef32_pk_fp4_f32 v252, v198, v199, 1.0 op_sel:[0,0,1,1]
	v_cvt_scalef32_pk_fp4_f32 v253, v206, v207, 1.0 op_sel:[0,0,1,1]
	v_readlane_b32 s88, v244, 28
	v_readlane_b32 s89, v244, 29
	s_lshl_b32 s96, s84, 9
	s_nop 1
	s_add_u32 s88, s88, 0x4280000
	s_addc_u32 s89, s89, 0
	s_add_u32 s88, s88, s96
	s_addc_u32 s89, s89, 0
	s_nop 0
	global_store_dwordx2 v255, v[252:253], s[88:89]
	v_readlane_b32 s88, v244, 28
	v_readlane_b32 s89, v244, 29
	s_lshl_b32 s96, s84, 2
	s_nop 1
	s_add_u32 s88, s88, 0xa310800
	s_addc_u32 s89, s89, 0
	s_add_u32 s88, s88, s96
	s_addc_u32 s89, s89, 0
	s_mov_b64 exec, 1
	global_store_dword v251, v250, s[88:89]
	s_mov_b64 exec, -1
	s_add_u32 s86, s86, s85
	s_min_u32 s87, s86, s90
	s_and_b32 s96, s87, 0x4000
	s_cmp_eq_u32 s96, 0
	s_cselect_b32 s94, s98, s100
	s_cselect_b32 s95, s99, s101
	s_and_b32 s96, s87, 0x3fff
	s_lshl_b32 s96, s96, 12
	s_add_u32 s94, s94, s96
	s_addc_u32 s95, s95, 0
	s_lshr_b32 s96, s87, 15
	s_lshl_b32 s96, s96, 26
	s_add_u32 s94, s94, s96
	s_addc_u32 s95, s95, 0
	global_load_dwordx4 v[176:179], v254, s[94:95] nt
	global_load_dwordx4 v[180:183], v254, s[94:95] offset:16 nt
	global_load_dwordx4 v[184:187], v254, s[94:95] offset:32 nt
	global_load_dwordx4 v[188:191], v254, s[94:95] offset:48 nt
	s_add_u32 s84, s84, s85
	s_cmp_ge_u32 s84, 0xc900
	s_cbranch_scc1 .Ltc_p15_done
	s_waitcnt vmcnt(12)
	v_max_f32_e64 v240, |v208|, |v209|
	v_max3_f32 v240, |v210|, |v211|, v240
	v_max3_f32 v240, |v212|, |v213|, v240
	v_max3_f32 v240, |v214|, |v215|, v240
	v_max3_f32 v240, |v216|, |v217|, v240
	v_max3_f32 v240, |v218|, |v219|, v240
	v_max3_f32 v240, |v220|, |v221|, v240
	v_max3_f32 v240, |v222|, |v223|, v240
	s_nop 1
	v_mov_b32_dpp v241, v240 quad_perm:[1,0,3,2] row_mask:0xf bank_mask:0xf bound_ctrl:1
	v_max_f32_e32 v241, v241, v241
	v_max_f32_e32 v240, v240, v241
	s_nop 1
	v_mov_b32_dpp v241, v240 quad_perm:[2,3,0,1] row_mask:0xf bank_mask:0xf bound_ctrl:1
	v_max_f32_e32 v241, v241, v241
	v_max_f32_e32 v240, v240, v241
	s_nop 1
	v_mov_b32_dpp v241, v240 row_half_mirror row_mask:0xf bank_mask:0xf bound_ctrl:1
	v_max_f32_e32 v241, v241, v241
	v_max_f32_e32 v240, v240, v241
	s_nop 1
	v_mov_b32_dpp v241, v240 row_mirror row_mask:0xf bank_mask:0xf bound_ctrl:1
	v_max_f32_e32 v241, v241, v241
	v_max_f32_e32 v240, v240, v241
	s_nop 0
	v_readlane_b32 s96, v240, 32
	v_readlane_b32 s97, v240, 48
	v_readlane_b32 s92, v240, 0
	v_readlane_b32 s93, v240, 16
	s_nop 1
	v_max_f32_e64 v240, s97, s97
	v_max_f32_e64 v241, s96, s96
	v_mov_b32_e32 v248, s93
	v_max_f32_e32 v240, v241, v240
	v_max3_f32 v240, s92, v248, v240
	v_div_scale_f32 v243, s[92:93], v240, v240, s91
	v_rcp_f32_e32 v246, v243
	v_div_scale_f32 v247, vcc, s91, v240, s91
	v_fma_f32 v248, -v243, v246, 1.0
	v_fmac_f32_e32 v246, v248, v246
	v_mul_f32_e32 v249, v247, v246
	v_fma_f32 v248, -v243, v249, v247
	v_fmac_f32_e32 v249, v248, v246
	v_fma_f32 v248, -v243, v249, v247
	v_div_fmas_f32 v242, v248, v246, v249
	v_div_fixup_f32 v242, v242, v240, s91
	v_cmp_lt_f32_e32 vcc, 0, v240
	v_mov_b32_e32 v252, 0
	v_mov_b32_e32 v253, 0
	v_cndmask_b32_e32 v242, 0, v242, vcc
	v_mul_f32_e32 v250, 0x3e2aaaab, v240
	v_mul_f32_e32 v208, v208, v242
	v_mul_f32_e32 v209, v209, v242
	v_mul_f32_e32 v210, v210, v242
	v_mul_f32_e32 v211, v211, v242
	v_mul_f32_e32 v212, v212, v242
	v_mul_f32_e32 v213, v213, v242
	v_mul_f32_e32 v214, v214, v242
	v_mul_f32_e32 v215, v215, v242
	v_mul_f32_e32 v216, v216, v242
	v_mul_f32_e32 v217, v217, v242
	v_mul_f32_e32 v218, v218, v242
	v_mul_f32_e32 v219, v219, v242
	v_mul_f32_e32 v220, v220, v242
	v_mul_f32_e32 v221, v221, v242
	v_mul_f32_e32 v222, v222, v242
	v_mul_f32_e32 v223, v223, v242
	v_cvt_scalef32_pk_fp4_f32 v252, v208, v209, 1.0
	v_cvt_scalef32_pk_fp4_f32 v253, v216, v217, 1.0
	v_cvt_scalef32_pk_fp4_f32 v252, v210, v211, 1.0 op_sel:[0,0,1,0]
	v_cvt_scalef32_pk_fp4_f32 v253, v218, v219, 1.0 op_sel:[0,0,1,0]
	v_cvt_scalef32_pk_fp4_f32 v252, v212, v213, 1.0 op_sel:[0,0,0,1]
	v_cvt_scalef32_pk_fp4_f32 v253, v220, v221, 1.0 op_sel:[0,0,0,1]
	v_cvt_scalef32_pk_fp4_f32 v252, v214, v215, 1.0 op_sel:[0,0,1,1]
	v_cvt_scalef32_pk_fp4_f32 v253, v222, v223, 1.0 op_sel:[0,0,1,1]
	v_readlane_b32 s88, v244, 28
	v_readlane_b32 s89, v244, 29
	s_lshl_b32 s96, s84, 9
	s_nop 1
	s_add_u32 s88, s88, 0x4280000
	s_addc_u32 s89, s89, 0
	s_add_u32 s88, s88, s96
	s_addc_u32 s89, s89, 0
	s_nop 0
	global_store_dwordx2 v255, v[252:253], s[88:89]
	v_readlane_b32 s88, v244, 28
	v_readlane_b32 s89, v244, 29
	s_lshl_b32 s96, s84, 2
	s_nop 1
	s_add_u32 s88, s88, 0xa310800
	s_addc_u32 s89, s89, 0
	s_add_u32 s88, s88, s96
	s_addc_u32 s89, s89, 0
	s_mov_b64 exec, 1
	global_store_dword v251, v250, s[88:89]
	s_mov_b64 exec, -1
	s_add_u32 s86, s86, s85
	s_min_u32 s87, s86, s90
	s_and_b32 s96, s87, 0x4000
	s_cmp_eq_u32 s96, 0
	s_cselect_b32 s94, s98, s100
	s_cselect_b32 s95, s99, s101
	s_and_b32 s96, s87, 0x3fff
	s_lshl_b32 s96, s96, 12
	s_add_u32 s94, s94, s96
	s_addc_u32 s95, s95, 0
	s_lshr_b32 s96, s87, 15
	s_lshl_b32 s96, s96, 26
	s_add_u32 s94, s94, s96
	s_addc_u32 s95, s95, 0
	global_load_dwordx4 v[192:195], v254, s[94:95] nt
	global_load_dwordx4 v[196:199], v254, s[94:95] offset:16 nt
	global_load_dwordx4 v[200:203], v254, s[94:95] offset:32 nt
	global_load_dwordx4 v[204:207], v254, s[94:95] offset:48 nt
	s_add_u32 s84, s84, s85
	s_cmp_ge_u32 s84, 0xc900
	s_cbranch_scc1 .Ltc_p15_done
	s_waitcnt vmcnt(12)
	v_max_f32_e64 v240, |v224|, |v225|
	v_max3_f32 v240, |v226|, |v227|, v240
	v_max3_f32 v240, |v228|, |v229|, v240
	v_max3_f32 v240, |v230|, |v231|, v240
	v_max3_f32 v240, |v232|, |v233|, v240
	v_max3_f32 v240, |v234|, |v235|, v240
	v_max3_f32 v240, |v236|, |v237|, v240
	v_max3_f32 v240, |v238|, |v239|, v240
	s_nop 1
	v_mov_b32_dpp v241, v240 quad_perm:[1,0,3,2] row_mask:0xf bank_mask:0xf bound_ctrl:1
	v_max_f32_e32 v241, v241, v241
	v_max_f32_e32 v240, v240, v241
	s_nop 1
	v_mov_b32_dpp v241, v240 quad_perm:[2,3,0,1] row_mask:0xf bank_mask:0xf bound_ctrl:1
	v_max_f32_e32 v241, v241, v241
	v_max_f32_e32 v240, v240, v241
	s_nop 1
	v_mov_b32_dpp v241, v240 row_half_mirror row_mask:0xf bank_mask:0xf bound_ctrl:1
	v_max_f32_e32 v241, v241, v241
	v_max_f32_e32 v240, v240, v241
	s_nop 1
	v_mov_b32_dpp v241, v240 row_mirror row_mask:0xf bank_mask:0xf bound_ctrl:1
	v_max_f32_e32 v241, v241, v241
	v_max_f32_e32 v240, v240, v241
	s_nop 0
	v_readlane_b32 s96, v240, 32
	v_readlane_b32 s97, v240, 48
	v_readlane_b32 s92, v240, 0
	v_readlane_b32 s93, v240, 16
	s_nop 1
	v_max_f32_e64 v240, s97, s97
	v_max_f32_e64 v241, s96, s96
	v_mov_b32_e32 v248, s93
	v_max_f32_e32 v240, v241, v240
	v_max3_f32 v240, s92, v248, v240
	v_div_scale_f32 v243, s[92:93], v240, v240, s91
	v_rcp_f32_e32 v246, v243
	v_div_scale_f32 v247, vcc, s91, v240, s91
	v_fma_f32 v248, -v243, v246, 1.0
	v_fmac_f32_e32 v246, v248, v246
	v_mul_f32_e32 v249, v247, v246
	v_fma_f32 v248, -v243, v249, v247
	v_fmac_f32_e32 v249, v248, v246
	v_fma_f32 v248, -v243, v249, v247
	v_div_fmas_f32 v242, v248, v246, v249
	v_div_fixup_f32 v242, v242, v240, s91
	v_cmp_lt_f32_e32 vcc, 0, v240
	v_mov_b32_e32 v252, 0
	v_mov_b32_e32 v253, 0
	v_cndmask_b32_e32 v242, 0, v242, vcc
	v_mul_f32_e32 v250, 0x3e2aaaab, v240
	v_mul_f32_e32 v224, v224, v242
	v_mul_f32_e32 v225, v225, v242
	v_mul_f32_e32 v226, v226, v242
	v_mul_f32_e32 v227, v227, v242
	v_mul_f32_e32 v228, v228, v242
	v_mul_f32_e32 v229, v229, v242
	v_mul_f32_e32 v230, v230, v242
	v_mul_f32_e32 v231, v231, v242
	v_mul_f32_e32 v232, v232, v242
	v_mul_f32_e32 v233, v233, v242
	v_mul_f32_e32 v234, v234, v242
	v_mul_f32_e32 v235, v235, v242
	v_mul_f32_e32 v236, v236, v242
	v_mul_f32_e32 v237, v237, v242
	v_mul_f32_e32 v238, v238, v242
	v_mul_f32_e32 v239, v239, v242
	v_cvt_scalef32_pk_fp4_f32 v252, v224, v225, 1.0
	v_cvt_scalef32_pk_fp4_f32 v253, v232, v233, 1.0
	v_cvt_scalef32_pk_fp4_f32 v252, v226, v227, 1.0 op_sel:[0,0,1,0]
	v_cvt_scalef32_pk_fp4_f32 v253, v234, v235, 1.0 op_sel:[0,0,1,0]
	v_cvt_scalef32_pk_fp4_f32 v252, v228, v229, 1.0 op_sel:[0,0,0,1]
	v_cvt_scalef32_pk_fp4_f32 v253, v236, v237, 1.0 op_sel:[0,0,0,1]
	v_cvt_scalef32_pk_fp4_f32 v252, v230, v231, 1.0 op_sel:[0,0,1,1]
	v_cvt_scalef32_pk_fp4_f32 v253, v238, v239, 1.0 op_sel:[0,0,1,1]
	v_readlane_b32 s88, v244, 28
	v_readlane_b32 s89, v244, 29
	s_lshl_b32 s96, s84, 9
	s_nop 1
	s_add_u32 s88, s88, 0x4280000
	s_addc_u32 s89, s89, 0
	s_add_u32 s88, s88, s96
	s_addc_u32 s89, s89, 0
	s_nop 0
	global_store_dwordx2 v255, v[252:253], s[88:89]
	v_readlane_b32 s88, v244, 28
	v_readlane_b32 s89, v244, 29
	s_lshl_b32 s96, s84, 2
	s_nop 1
	s_add_u32 s88, s88, 0xa310800
	s_addc_u32 s89, s89, 0
	s_add_u32 s88, s88, s96
	s_addc_u32 s89, s89, 0
	s_mov_b64 exec, 1
	global_store_dword v251, v250, s[88:89]
	s_mov_b64 exec, -1
	s_add_u32 s86, s86, s85
	s_min_u32 s87, s86, s90
	s_and_b32 s96, s87, 0x4000
	s_cmp_eq_u32 s96, 0
	s_cselect_b32 s94, s98, s100
	s_cselect_b32 s95, s99, s101
	s_and_b32 s96, s87, 0x3fff
	s_lshl_b32 s96, s96, 12
	s_add_u32 s94, s94, s96
	s_addc_u32 s95, s95, 0
	s_lshr_b32 s96, s87, 15
	s_lshl_b32 s96, s96, 26
	s_add_u32 s94, s94, s96
	s_addc_u32 s95, s95, 0
	global_load_dwordx4 v[208:211], v254, s[94:95] nt
	global_load_dwordx4 v[212:215], v254, s[94:95] offset:16 nt
	global_load_dwordx4 v[216:219], v254, s[94:95] offset:32 nt
	global_load_dwordx4 v[220:223], v254, s[94:95] offset:48 nt
	s_add_u32 s84, s84, s85
	s_branch .Ltc_p15_loop

.Ltc_p15_end:
.LBB0_2945:
	v_readlane_b32 s4, v245, 7
	v_readlane_b32 s5, v245, 8
	s_cmp_gt_i32 s4, 16
	s_cselect_b64 s[0:1], -1, 0
	s_cmp_lt_i32 s5, 17
	s_cselect_b64 s[2:3], -1, 0
	s_or_b64 s[2:3], s[0:1], s[2:3]
	s_and_b64 vcc, exec, s[2:3]
	v_readlane_b32 s6, v245, 9
	v_readlane_b32 s7, v245, 10
	s_cbranch_vccnz .LBB0_3015
	s_andn2_b64 vcc, exec, s[12:13]
	s_cbranch_vccnz .LBB0_2948
	v_and_b32_e32 v1, 0x3ff, v0
	s_cbranch_execz .LBB0_2949
	s_branch .LBB0_3011

.Ltc_p17:
	s_mov_b64 exec, -1
	v_readlane_b32 s84, v245, 0
	s_nop 3
	s_and_b32 s97, s84, 0xff
	s_cmp_lt_u32 s97, 80
	s_cbranch_scc1 .Ltc_p17_end
	v_and_b32_e32 v255, 63, v0
	v_lshlrev_b32_e32 v254, 6, v255
	v_lshlrev_b32_e32 v255, 3, v255
	v_mov_b32_e32 v251, 0
	v_readfirstlane_b32 s96, v0
	v_readlane_b32 s98, v244, 22
	v_readlane_b32 s99, v244, 23
	v_readlane_b32 s100, v244, 24
	v_readlane_b32 s101, v244, 25
	s_nop 3
	s_and_b32 s96, s96, 0x3ff
	s_lshr_b32 s96, s96, 6
	s_sub_u32 s97, s97, 80
	s_lshr_b32 s84, s84, 8
	s_mul_i32 s84, s84, 176
	s_add_u32 s84, s84, s97
	s_lshl_b32 s84, s84, 2
	s_add_u32 s84, s84, s96
	s_add_u32 s84, s84, 0xc900
	s_mov_b32 s85, 1408
	s_mov_b32 s91, 0x40c00000
	s_cmp_ge_u32 s84, 0x10000
	s_cbranch_scc1 .Ltc_p17_end
	s_mov_b32 s90, s84
.Ltc_p17_last:
	s_add_u32 s87, s90, s85
	s_cmp_ge_u32 s87, 0x10000
	s_cbranch_scc1 .Ltc_p17_lastd
	s_mov_b32 s90, s87
	s_branch .Ltc_p17_last

.Ltc_p17_loop:
	s_cmp_ge_u32 s84, 0x10000
	s_cbranch_scc1 .Ltc_p17_done
	s_waitcnt vmcnt(12)
	v_max_f32_e64 v240, |v176|, |v177|
	v_max3_f32 v240, |v178|, |v179|, v240
	v_max3_f32 v240, |v180|, |v181|, v240
	v_max3_f32 v240, |v182|, |v183|, v240
	v_max3_f32 v240, |v184|, |v185|, v240
	v_max3_f32 v240, |v186|, |v187|, v240
	v_max3_f32 v240, |v188|, |v189|, v240
	v_max3_f32 v240, |v190|, |v191|, v240
	s_nop 1
	v_mov_b32_dpp v241, v240 quad_perm:[1,0,3,2] row_mask:0xf bank_mask:0xf bound_ctrl:1
	v_max_f32_e32 v241, v241, v241
	v_max_f32_e32 v240, v240, v241
	s_nop 1
	v_mov_b32_dpp v241, v240 quad_perm:[2,3,0,1] row_mask:0xf bank_mask:0xf bound_ctrl:1
	v_max_f32_e32 v241, v241, v241
	v_max_f32_e32 v240, v240, v241
	s_nop 1
	v_mov_b32_dpp v241, v240 row_half_mirror row_mask:0xf bank_mask:0xf bound_ctrl:1
	v_max_f32_e32 v241, v241, v241
	v_max_f32_e32 v240, v240, v241
	s_nop 1
	v_mov_b32_dpp v241, v240 row_mirror row_mask:0xf bank_mask:0xf bound_ctrl:1
	v_max_f32_e32 v241, v241, v241
	v_max_f32_e32 v240, v240, v241
	s_nop 0
	v_readlane_b32 s96, v240, 32
	v_readlane_b32 s97, v240, 48
	v_readlane_b32 s92, v240, 0
	v_readlane_b32 s93, v240, 16
	s_nop 1
	v_max_f32_e64 v240, s97, s97
	v_max_f32_e64 v241, s96, s96
	v_mov_b32_e32 v248, s93
	v_max_f32_e32 v240, v241, v240
	v_max3_f32 v240, s92, v248, v240
	v_div_scale_f32 v243, s[92:93], v240, v240, s91
	v_rcp_f32_e32 v246, v243
	v_div_scale_f32 v247, vcc, s91, v240, s91
	v_fma_f32 v248, -v243, v246, 1.0
	v_fmac_f32_e32 v246, v248, v246
	v_mul_f32_e32 v249, v247, v246
	v_fma_f32 v248, -v243, v249, v247
	v_fmac_f32_e32 v249, v248, v246
	v_fma_f32 v248, -v243, v249, v247
	v_div_fmas_f32 v242, v248, v246, v249
	v_div_fixup_f32 v242, v242, v240, s91
	v_cmp_lt_f32_e32 vcc, 0, v240
	v_mov_b32_e32 v252, 0
	v_mov_b32_e32 v253, 0
	v_cndmask_b32_e32 v242, 0, v242, vcc
	v_mul_f32_e32 v250, 0x3e2aaaab, v240
	v_mul_f32_e32 v176, v176, v242
	v_mul_f32_e32 v177, v177, v242
	v_mul_f32_e32 v178, v178, v242
	v_mul_f32_e32 v179, v179, v242
	v_mul_f32_e32 v180, v180, v242
	v_mul_f32_e32 v181, v181, v242
	v_mul_f32_e32 v182, v182, v242
	v_mul_f32_e32 v183, v183, v242
	v_mul_f32_e32 v184, v184, v242
	v_mul_f32_e32 v185, v185, v242
	v_mul_f32_e32 v186, v186, v242
	v_mul_f32_e32 v187, v187, v242
	v_mul_f32_e32 v188, v188, v242
	v_mul_f32_e32 v189, v189, v242
	v_mul_f32_e32 v190, v190, v242
	v_mul_f32_e32 v191, v191, v242
	v_cvt_scalef32_pk_fp4_f32 v252, v176, v177, 1.0
	v_cvt_scalef32_pk_fp4_f32 v253, v184, v185, 1.0
	v_cvt_scalef32_pk_fp4_f32 v252, v178, v179, 1.0 op_sel:[0,0,1,0]
	v_cvt_scalef32_pk_fp4_f32 v253, v186, v187, 1.0 op_sel:[0,0,1,0]
	v_cvt_scalef32_pk_fp4_f32 v252, v180, v181, 1.0 op_sel:[0,0,0,1]
	v_cvt_scalef32_pk_fp4_f32 v253, v188, v189, 1.0 op_sel:[0,0,0,1]
	v_cvt_scalef32_pk_fp4_f32 v252, v182, v183, 1.0 op_sel:[0,0,1,1]
	v_cvt_scalef32_pk_fp4_f32 v253, v190, v191, 1.0 op_sel:[0,0,1,1]
	v_readlane_b32 s88, v244, 28
	v_readlane_b32 s89, v244, 29
	s_lshl_b32 s96, s84, 9
	s_nop 1
	s_add_u32 s88, s88, 0x4280000
	s_addc_u32 s89, s89, 0
	s_add_u32 s88, s88, s96
	s_addc_u32 s89, s89, 0
	s_nop 0
	global_store_dwordx2 v255, v[252:253], s[88:89]
	v_readlane_b32 s88, v244, 28
	v_readlane_b32 s89, v244, 29
	s_lshl_b32 s96, s84, 2
	s_nop 1
	s_add_u32 s88, s88, 0xa310800
	s_addc_u32 s89, s89, 0
	s_add_u32 s88, s88, s96
	s_addc_u32 s89, s89, 0
	s_mov_b64 exec, 1
	global_store_dword v251, v250, s[88:89]
	s_mov_b64 exec, -1
	s_add_u32 s86, s86, s85
	s_min_u32 s87, s86, s90
	s_and_b32 s96, s87, 0x4000
	s_cmp_eq_u32 s96, 0
	s_cselect_b32 s94, s98, s100
	s_cselect_b32 s95, s99, s101
	s_and_b32 s96, s87, 0x3fff
	s_lshl_b32 s96, s96, 12
	s_add_u32 s94, s94, s96
	s_addc_u32 s95, s95, 0
	s_lshr_b32 s96, s87, 15
	s_lshl_b32 s96, s96, 26
	s_add_u32 s94, s94, s96
	s_addc_u32 s95, s95, 0
	global_load_dwordx4 v[224:227], v254, s[94:95] nt
	global_load_dwordx4 v[228:231], v254, s[94:95] offset:16 nt
	global_load_dwordx4 v[232:235], v254, s[94:95] offset:32 nt
	global_load_dwordx4 v[236:239], v254, s[94:95] offset:48 nt
	s_add_u32 s84, s84, s85
	s_cmp_ge_u32 s84, 0x10000
	s_cbranch_scc1 .Ltc_p17_done
	s_waitcnt vmcnt(12)
	v_max_f32_e64 v240, |v192|, |v193|
	v_max3_f32 v240, |v194|, |v195|, v240
	v_max3_f32 v240, |v196|, |v197|, v240
	v_max3_f32 v240, |v198|, |v199|, v240
	v_max3_f32 v240, |v200|, |v201|, v240
	v_max3_f32 v240, |v202|, |v203|, v240
	v_max3_f32 v240, |v204|, |v205|, v240
	v_max3_f32 v240, |v206|, |v207|, v240
	s_nop 1
	v_mov_b32_dpp v241, v240 quad_perm:[1,0,3,2] row_mask:0xf bank_mask:0xf bound_ctrl:1
	v_max_f32_e32 v241, v241, v241
	v_max_f32_e32 v240, v240, v241
	s_nop 1
	v_mov_b32_dpp v241, v240 quad_perm:[2,3,0,1] row_mask:0xf bank_mask:0xf bound_ctrl:1
	v_max_f32_e32 v241, v241, v241
	v_max_f32_e32 v240, v240, v241
	s_nop 1
	v_mov_b32_dpp v241, v240 row_half_mirror row_mask:0xf bank_mask:0xf bound_ctrl:1
	v_max_f32_e32 v241, v241, v241
	v_max_f32_e32 v240, v240, v241
	s_nop 1
	v_mov_b32_dpp v241, v240 row_mirror row_mask:0xf bank_mask:0xf bound_ctrl:1
	v_max_f32_e32 v241, v241, v241
	v_max_f32_e32 v240, v240, v241
	s_nop 0
	v_readlane_b32 s96, v240, 32
	v_readlane_b32 s97, v240, 48
	v_readlane_b32 s92, v240, 0
	v_readlane_b32 s93, v240, 16
	s_nop 1
	v_max_f32_e64 v240, s97, s97
	v_max_f32_e64 v241, s96, s96
	v_mov_b32_e32 v248, s93
	v_max_f32_e32 v240, v241, v240
	v_max3_f32 v240, s92, v248, v240
	v_div_scale_f32 v243, s[92:93], v240, v240, s91
	v_rcp_f32_e32 v246, v243
	v_div_scale_f32 v247, vcc, s91, v240, s91
	v_fma_f32 v248, -v243, v246, 1.0
	v_fmac_f32_e32 v246, v248, v246
	v_mul_f32_e32 v249, v247, v246
	v_fma_f32 v248, -v243, v249, v247
	v_fmac_f32_e32 v249, v248, v246
	v_fma_f32 v248, -v243, v249, v247
	v_div_fmas_f32 v242, v248, v246, v249
	v_div_fixup_f32 v242, v242, v240, s91
	v_cmp_lt_f32_e32 vcc, 0, v240
	v_mov_b32_e32 v252, 0
	v_mov_b32_e32 v253, 0
	v_cndmask_b32_e32 v242, 0, v242, vcc
	v_mul_f32_e32 v250, 0x3e2aaaab, v240
	v_mul_f32_e32 v192, v192, v242
	v_mul_f32_e32 v193, v193, v242
	v_mul_f32_e32 v194, v194, v242
	v_mul_f32_e32 v195, v195, v242
	v_mul_f32_e32 v196, v196, v242
	v_mul_f32_e32 v197, v197, v242
	v_mul_f32_e32 v198, v198, v242
	v_mul_f32_e32 v199, v199, v242
	v_mul_f32_e32 v200, v200, v242
	v_mul_f32_e32 v201, v201, v242
	v_mul_f32_e32 v202, v202, v242
	v_mul_f32_e32 v203, v203, v242
	v_mul_f32_e32 v204, v204, v242
	v_mul_f32_e32 v205, v205, v242
	v_mul_f32_e32 v206, v206, v242
	v_mul_f32_e32 v207, v207, v242
	v_cvt_scalef32_pk_fp4_f32 v252, v192, v193, 1.0
	v_cvt_scalef32_pk_fp4_f32 v253, v200, v201, 1.0
	v_cvt_scalef32_pk_fp4_f32 v252, v194, v195, 1.0 op_sel:[0,0,1,0]
	v_cvt_scalef32_pk_fp4_f32 v253, v202, v203, 1.0 op_sel:[0,0,1,0]
	v_cvt_scalef32_pk_fp4_f32 v252, v196, v197, 1.0 op_sel:[0,0,0,1]
	v_cvt_scalef32_pk_fp4_f32 v253, v204, v205, 1.0 op_sel:[0,0,0,1]
	v_cvt_scalef32_pk_fp4_f32 v252, v198, v199, 1.0 op_sel:[0,0,1,1]
	v_cvt_scalef32_pk_fp4_f32 v253, v206, v207, 1.0 op_sel:[0,0,1,1]
	v_readlane_b32 s88, v244, 28
	v_readlane_b32 s89, v244, 29
	s_lshl_b32 s96, s84, 9
	s_nop 1
	s_add_u32 s88, s88, 0x4280000
	s_addc_u32 s89, s89, 0
	s_add_u32 s88, s88, s96
	s_addc_u32 s89, s89, 0
	s_nop 0
	global_store_dwordx2 v255, v[252:253], s[88:89]
	v_readlane_b32 s88, v244, 28
	v_readlane_b32 s89, v244, 29
	s_lshl_b32 s96, s84, 2
	s_nop 1
	s_add_u32 s88, s88, 0xa310800
	s_addc_u32 s89, s89, 0
	s_add_u32 s88, s88, s96
	s_addc_u32 s89, s89, 0
	s_mov_b64 exec, 1
	global_store_dword v251, v250, s[88:89]
	s_mov_b64 exec, -1
	s_add_u32 s86, s86, s85
	s_min_u32 s87, s86, s90
	s_and_b32 s96, s87, 0x4000
	s_cmp_eq_u32 s96, 0
	s_cselect_b32 s94, s98, s100
	s_cselect_b32 s95, s99, s101
	s_and_b32 s96, s87, 0x3fff
	s_lshl_b32 s96, s96, 12
	s_add_u32 s94, s94, s96
	s_addc_u32 s95, s95, 0
	s_lshr_b32 s96, s87, 15
	s_lshl_b32 s96, s96, 26
	s_add_u32 s94, s94, s96
	s_addc_u32 s95, s95, 0
	global_load_dwordx4 v[176:179], v254, s[94:95] nt
	global_load_dwordx4 v[180:183], v254, s[94:95] offset:16 nt
	global_load_dwordx4 v[184:187], v254, s[94:95] offset:32 nt
	global_load_dwordx4 v[188:191], v254, s[94:95] offset:48 nt
	s_add_u32 s84, s84, s85
	s_cmp_ge_u32 s84, 0x10000
	s_cbranch_scc1 .Ltc_p17_done
	s_waitcnt vmcnt(12)
	v_max_f32_e64 v240, |v208|, |v209|
	v_max3_f32 v240, |v210|, |v211|, v240
	v_max3_f32 v240, |v212|, |v213|, v240
	v_max3_f32 v240, |v214|, |v215|, v240
	v_max3_f32 v240, |v216|, |v217|, v240
	v_max3_f32 v240, |v218|, |v219|, v240
	v_max3_f32 v240, |v220|, |v221|, v240
	v_max3_f32 v240, |v222|, |v223|, v240
	s_nop 1
	v_mov_b32_dpp v241, v240 quad_perm:[1,0,3,2] row_mask:0xf bank_mask:0xf bound_ctrl:1
	v_max_f32_e32 v241, v241, v241
	v_max_f32_e32 v240, v240, v241
	s_nop 1
	v_mov_b32_dpp v241, v240 quad_perm:[2,3,0,1] row_mask:0xf bank_mask:0xf bound_ctrl:1
	v_max_f32_e32 v241, v241, v241
	v_max_f32_e32 v240, v240, v241
	s_nop 1
	v_mov_b32_dpp v241, v240 row_half_mirror row_mask:0xf bank_mask:0xf bound_ctrl:1
	v_max_f32_e32 v241, v241, v241
	v_max_f32_e32 v240, v240, v241
	s_nop 1
	v_mov_b32_dpp v241, v240 row_mirror row_mask:0xf bank_mask:0xf bound_ctrl:1
	v_max_f32_e32 v241, v241, v241
	v_max_f32_e32 v240, v240, v241
	s_nop 0
	v_readlane_b32 s96, v240, 32
	v_readlane_b32 s97, v240, 48
	v_readlane_b32 s92, v240, 0
	v_readlane_b32 s93, v240, 16
	s_nop 1
	v_max_f32_e64 v240, s97, s97
	v_max_f32_e64 v241, s96, s96
	v_mov_b32_e32 v248, s93
	v_max_f32_e32 v240, v241, v240
	v_max3_f32 v240, s92, v248, v240
	v_div_scale_f32 v243, s[92:93], v240, v240, s91
	v_rcp_f32_e32 v246, v243
	v_div_scale_f32 v247, vcc, s91, v240, s91
	v_fma_f32 v248, -v243, v246, 1.0
	v_fmac_f32_e32 v246, v248, v246
	v_mul_f32_e32 v249, v247, v246
	v_fma_f32 v248, -v243, v249, v247
	v_fmac_f32_e32 v249, v248, v246
	v_fma_f32 v248, -v243, v249, v247
	v_div_fmas_f32 v242, v248, v246, v249
	v_div_fixup_f32 v242, v242, v240, s91
	v_cmp_lt_f32_e32 vcc, 0, v240
	v_mov_b32_e32 v252, 0
	v_mov_b32_e32 v253, 0
	v_cndmask_b32_e32 v242, 0, v242, vcc
	v_mul_f32_e32 v250, 0x3e2aaaab, v240
	v_mul_f32_e32 v208, v208, v242
	v_mul_f32_e32 v209, v209, v242
	v_mul_f32_e32 v210, v210, v242
	v_mul_f32_e32 v211, v211, v242
	v_mul_f32_e32 v212, v212, v242
	v_mul_f32_e32 v213, v213, v242
	v_mul_f32_e32 v214, v214, v242
	v_mul_f32_e32 v215, v215, v242
	v_mul_f32_e32 v216, v216, v242
	v_mul_f32_e32 v217, v217, v242
	v_mul_f32_e32 v218, v218, v242
	v_mul_f32_e32 v219, v219, v242
	v_mul_f32_e32 v220, v220, v242
	v_mul_f32_e32 v221, v221, v242
	v_mul_f32_e32 v222, v222, v242
	v_mul_f32_e32 v223, v223, v242
	v_cvt_scalef32_pk_fp4_f32 v252, v208, v209, 1.0
	v_cvt_scalef32_pk_fp4_f32 v253, v216, v217, 1.0
	v_cvt_scalef32_pk_fp4_f32 v252, v210, v211, 1.0 op_sel:[0,0,1,0]
	v_cvt_scalef32_pk_fp4_f32 v253, v218, v219, 1.0 op_sel:[0,0,1,0]
	v_cvt_scalef32_pk_fp4_f32 v252, v212, v213, 1.0 op_sel:[0,0,0,1]
	v_cvt_scalef32_pk_fp4_f32 v253, v220, v221, 1.0 op_sel:[0,0,0,1]
	v_cvt_scalef32_pk_fp4_f32 v252, v214, v215, 1.0 op_sel:[0,0,1,1]
	v_cvt_scalef32_pk_fp4_f32 v253, v222, v223, 1.0 op_sel:[0,0,1,1]
	v_readlane_b32 s88, v244, 28
	v_readlane_b32 s89, v244, 29
	s_lshl_b32 s96, s84, 9
	s_nop 1
	s_add_u32 s88, s88, 0x4280000
	s_addc_u32 s89, s89, 0
	s_add_u32 s88, s88, s96
	s_addc_u32 s89, s89, 0
	s_nop 0
	global_store_dwordx2 v255, v[252:253], s[88:89]
	v_readlane_b32 s88, v244, 28
	v_readlane_b32 s89, v244, 29
	s_lshl_b32 s96, s84, 2
	s_nop 1
	s_add_u32 s88, s88, 0xa310800
	s_addc_u32 s89, s89, 0
	s_add_u32 s88, s88, s96
	s_addc_u32 s89, s89, 0
	s_mov_b64 exec, 1
	global_store_dword v251, v250, s[88:89]
	s_mov_b64 exec, -1
	s_add_u32 s86, s86, s85
	s_min_u32 s87, s86, s90
	s_and_b32 s96, s87, 0x4000
	s_cmp_eq_u32 s96, 0
	s_cselect_b32 s94, s98, s100
	s_cselect_b32 s95, s99, s101
	s_and_b32 s96, s87, 0x3fff
	s_lshl_b32 s96, s96, 12
	s_add_u32 s94, s94, s96
	s_addc_u32 s95, s95, 0
	s_lshr_b32 s96, s87, 15
	s_lshl_b32 s96, s96, 26
	s_add_u32 s94, s94, s96
	s_addc_u32 s95, s95, 0
	global_load_dwordx4 v[192:195], v254, s[94:95] nt
	global_load_dwordx4 v[196:199], v254, s[94:95] offset:16 nt
	global_load_dwordx4 v[200:203], v254, s[94:95] offset:32 nt
	global_load_dwordx4 v[204:207], v254, s[94:95] offset:48 nt
	s_add_u32 s84, s84, s85
	s_cmp_ge_u32 s84, 0x10000
	s_cbranch_scc1 .Ltc_p17_done
	s_waitcnt vmcnt(12)
	v_max_f32_e64 v240, |v224|, |v225|
	v_max3_f32 v240, |v226|, |v227|, v240
	v_max3_f32 v240, |v228|, |v229|, v240
	v_max3_f32 v240, |v230|, |v231|, v240
	v_max3_f32 v240, |v232|, |v233|, v240
	v_max3_f32 v240, |v234|, |v235|, v240
	v_max3_f32 v240, |v236|, |v237|, v240
	v_max3_f32 v240, |v238|, |v239|, v240
	s_nop 1
	v_mov_b32_dpp v241, v240 quad_perm:[1,0,3,2] row_mask:0xf bank_mask:0xf bound_ctrl:1
	v_max_f32_e32 v241, v241, v241
	v_max_f32_e32 v240, v240, v241
	s_nop 1
	v_mov_b32_dpp v241, v240 quad_perm:[2,3,0,1] row_mask:0xf bank_mask:0xf bound_ctrl:1
	v_max_f32_e32 v241, v241, v241
	v_max_f32_e32 v240, v240, v241
	s_nop 1
	v_mov_b32_dpp v241, v240 row_half_mirror row_mask:0xf bank_mask:0xf bound_ctrl:1
	v_max_f32_e32 v241, v241, v241
	v_max_f32_e32 v240, v240, v241
	s_nop 1
	v_mov_b32_dpp v241, v240 row_mirror row_mask:0xf bank_mask:0xf bound_ctrl:1
	v_max_f32_e32 v241, v241, v241
	v_max_f32_e32 v240, v240, v241
	s_nop 0
	v_readlane_b32 s96, v240, 32
	v_readlane_b32 s97, v240, 48
	v_readlane_b32 s92, v240, 0
	v_readlane_b32 s93, v240, 16
	s_nop 1
	v_max_f32_e64 v240, s97, s97
	v_max_f32_e64 v241, s96, s96
	v_mov_b32_e32 v248, s93
	v_max_f32_e32 v240, v241, v240
	v_max3_f32 v240, s92, v248, v240
	v_div_scale_f32 v243, s[92:93], v240, v240, s91
	v_rcp_f32_e32 v246, v243
	v_div_scale_f32 v247, vcc, s91, v240, s91
	v_fma_f32 v248, -v243, v246, 1.0
	v_fmac_f32_e32 v246, v248, v246
	v_mul_f32_e32 v249, v247, v246
	v_fma_f32 v248, -v243, v249, v247
	v_fmac_f32_e32 v249, v248, v246
	v_fma_f32 v248, -v243, v249, v247
	v_div_fmas_f32 v242, v248, v246, v249
	v_div_fixup_f32 v242, v242, v240, s91
	v_cmp_lt_f32_e32 vcc, 0, v240
	v_mov_b32_e32 v252, 0
	v_mov_b32_e32 v253, 0
	v_cndmask_b32_e32 v242, 0, v242, vcc
	v_mul_f32_e32 v250, 0x3e2aaaab, v240
	v_mul_f32_e32 v224, v224, v242
	v_mul_f32_e32 v225, v225, v242
	v_mul_f32_e32 v226, v226, v242
	v_mul_f32_e32 v227, v227, v242
	v_mul_f32_e32 v228, v228, v242
	v_mul_f32_e32 v229, v229, v242
	v_mul_f32_e32 v230, v230, v242
	v_mul_f32_e32 v231, v231, v242
	v_mul_f32_e32 v232, v232, v242
	v_mul_f32_e32 v233, v233, v242
	v_mul_f32_e32 v234, v234, v242
	v_mul_f32_e32 v235, v235, v242
	v_mul_f32_e32 v236, v236, v242
	v_mul_f32_e32 v237, v237, v242
	v_mul_f32_e32 v238, v238, v242
	v_mul_f32_e32 v239, v239, v242
	v_cvt_scalef32_pk_fp4_f32 v252, v224, v225, 1.0
	v_cvt_scalef32_pk_fp4_f32 v253, v232, v233, 1.0
	v_cvt_scalef32_pk_fp4_f32 v252, v226, v227, 1.0 op_sel:[0,0,1,0]
	v_cvt_scalef32_pk_fp4_f32 v253, v234, v235, 1.0 op_sel:[0,0,1,0]
	v_cvt_scalef32_pk_fp4_f32 v252, v228, v229, 1.0 op_sel:[0,0,0,1]
	v_cvt_scalef32_pk_fp4_f32 v253, v236, v237, 1.0 op_sel:[0,0,0,1]
	v_cvt_scalef32_pk_fp4_f32 v252, v230, v231, 1.0 op_sel:[0,0,1,1]
	v_cvt_scalef32_pk_fp4_f32 v253, v238, v239, 1.0 op_sel:[0,0,1,1]
	v_readlane_b32 s88, v244, 28
	v_readlane_b32 s89, v244, 29
	s_lshl_b32 s96, s84, 9
	s_nop 1
	s_add_u32 s88, s88, 0x4280000
	s_addc_u32 s89, s89, 0
	s_add_u32 s88, s88, s96
	s_addc_u32 s89, s89, 0
	s_nop 0
	global_store_dwordx2 v255, v[252:253], s[88:89]
	v_readlane_b32 s88, v244, 28
	v_readlane_b32 s89, v244, 29
	s_lshl_b32 s96, s84, 2
	s_nop 1
	s_add_u32 s88, s88, 0xa310800
	s_addc_u32 s89, s89, 0
	s_add_u32 s88, s88, s96
	s_addc_u32 s89, s89, 0
	s_mov_b64 exec, 1
	global_store_dword v251, v250, s[88:89]
	s_mov_b64 exec, -1
	s_add_u32 s86, s86, s85
	s_min_u32 s87, s86, s90
	s_and_b32 s96, s87, 0x4000
	s_cmp_eq_u32 s96, 0
	s_cselect_b32 s94, s98, s100
	s_cselect_b32 s95, s99, s101
	s_and_b32 s96, s87, 0x3fff
	s_lshl_b32 s96, s96, 12
	s_add_u32 s94, s94, s96
	s_addc_u32 s95, s95, 0
	s_lshr_b32 s96, s87, 15
	s_lshl_b32 s96, s96, 26
	s_add_u32 s94, s94, s96
	s_addc_u32 s95, s95, 0
	global_load_dwordx4 v[208:211], v254, s[94:95] nt
	global_load_dwordx4 v[212:215], v254, s[94:95] offset:16 nt
	global_load_dwordx4 v[216:219], v254, s[94:95] offset:32 nt
	global_load_dwordx4 v[220:223], v254, s[94:95] offset:48 nt
	s_add_u32 s84, s84, s85
	s_branch .Ltc_p17_loop

.Ltc_p17_end:
.LBB0_3154:
	v_readlane_b32 s4, v245, 7
	v_readlane_b32 s5, v245, 8
	s_cmp_gt_i32 s4, 18
	s_cselect_b64 s[0:1], -1, 0
	s_cmp_lt_i32 s5, 19
	s_cselect_b64 s[2:3], -1, 0
	s_or_b64 s[2:3], s[0:1], s[2:3]
	s_and_b64 vcc, exec, s[2:3]
	v_readlane_b32 s6, v245, 9
	v_readlane_b32 s7, v245, 10
	s_cbranch_vccnz .LBB0_3224
	s_andn2_b64 vcc, exec, s[20:21]
	s_cbranch_vccnz .LBB0_3157
	v_and_b32_e32 v4, 0x3ff, v0
	s_cbranch_execz .LBB0_3158
	s_branch .LBB0_3220
